# stagger blocks>=256 by ~37us at phases 5,8,12,15
# baseline (speedup 1.0000x reference)
.LBB0_526:
	s_cmpk_lt_u32 s82, 0x100
	s_cbranch_scc1 .Lstag_5
	s_movk_i32 s100, 10
.Lstag_loop_5:
	s_sleep 127
	s_sub_u32 s100, s100, 1
	s_cmp_lg_u32 s100, 0
	s_cbranch_scc1 .Lstag_loop_5
